# k30: k27 + conv epilogue: third per-channel weight load issued with the first two (one wait instead of two) in one phase
# baseline (speedup 1.0000x reference)
.LBB0_286:
	v_lshl_add_u32 v212, s8, 8, v222
	v_or_b32_e32 v200, 16, v212
	v_ashrrev_i32_e32 v213, 31, v212
	v_ashrrev_i32_e32 v201, 31, v200
	v_or_b32_e32 v218, 32, v212
	v_or_b32_e32 v216, 48, v212
	v_lshl_add_u64 v[114:115], v[212:213], 4, s[76:77]
	v_lshl_add_u64 v[116:117], v[200:201], 4, s[76:77]
	v_ashrrev_i32_e32 v219, 31, v218
	v_ashrrev_i32_e32 v217, 31, v216
	v_add_u32_e32 v210, 0x80, v212
	v_add_u32_e32 v208, 0x90, v212
	v_add_u32_e32 v204, 0xa0, v212
	v_add_u32_e32 v202, 0xb0, v212
	global_load_dwordx4 v[154:157], v[114:115], off
	global_load_dwordx4 v[146:149], v[116:117], off
	v_lshl_add_u64 v[114:115], v[218:219], 4, s[76:77]
	v_lshl_add_u64 v[116:117], v[216:217], 4, s[76:77]
	v_ashrrev_i32_e32 v211, 31, v210
	v_ashrrev_i32_e32 v209, 31, v208
	v_ashrrev_i32_e32 v205, 31, v204
	v_ashrrev_i32_e32 v203, 31, v202
	global_load_dwordx4 v[166:169], v[114:115], off
	global_load_dwordx4 v[150:153], v[116:117], off
	v_lshl_add_u64 v[114:115], v[210:211], 4, s[76:77]
	v_lshl_add_u64 v[116:117], v[208:209], 4, s[76:77]
	v_lshl_add_u64 v[118:119], v[204:205], 4, s[76:77]
	v_lshl_add_u64 v[120:121], v[202:203], 4, s[76:77]
	global_load_dwordx4 v[122:125], v[114:115], off
	s_nop 0
	global_load_dwordx4 v[114:117], v[116:117], off
	s_nop 0
	global_load_dwordx4 v[126:129], v[118:119], off
	s_nop 0
	global_load_dwordx4 v[118:121], v[120:121], off
	s_lshl_b32 s36, s6, 8
	s_mov_b64 s[2:3], exec
	v_readlane_b32 s0, v254, 16
	v_readlane_b32 s1, v254, 17
	s_and_b64 s[0:1], s[2:3], s[0:1]
	s_mov_b64 exec, s[0:1]
	s_cbranch_execz .LBB0_288
	v_or_b32_e32 v158, s36, v0
	v_readlane_b32 s52, v254, 18
	v_ashrrev_i32_e32 v159, 31, v158
	v_readlane_b32 s64, v254, 30
	v_readlane_b32 s65, v254, 31
	v_readlane_b32 s53, v254, 19
	v_readlane_b32 s54, v254, 20
	v_lshl_add_u64 v[160:161], v[158:159], 2, s[64:65]
	global_load_dword v159, v[160:161], off
	v_add_u32_e32 v160, 0x400, v158
	v_ashrrev_i32_e32 v161, 31, v160
	v_lshl_add_u64 v[160:161], v[160:161], 2, s[64:65]
	global_load_dword v160, v[160:161], off
	v_add_u32_e32 v158, 0x800, v158
	v_ashrrev_i32_e32 v251, 31, v158
	v_mov_b32_e32 v250, v158
	v_lshl_add_u64 v[250:251], v[250:251], 2, s[64:65]
	global_load_dword v252, v[250:251], off
	v_readlane_b32 s55, v254, 21
	v_readlane_b32 s56, v254, 22
	v_readlane_b32 s57, v254, 23
	v_readlane_b32 s58, v254, 24
	v_readlane_b32 s59, v254, 25
	v_readlane_b32 s60, v254, 26
	v_readlane_b32 s61, v254, 27
	v_readlane_b32 s62, v254, 28
	v_readlane_b32 s63, v254, 29
	v_readlane_b32 s66, v254, 32
	v_readlane_b32 s67, v254, 33
	s_waitcnt vmcnt(0)
	ds_write2st64_b32 v225, v159, v160 offset1:4
	s_mov_b32 s64, s96
	ds_write_b32 v225, v252 offset:2048
